# RWKV operand prefetch distance 2; FoX items from a dynamic queue (LDS 80 KB)
# speedup vs baseline: 1.0050x; 1.0050x over previous
; __device__ __forceinline__ void mixer0_phase(const Params& p, float* sm, int bid, int nb) {
;     ...
;       for (int f = bid - 128; f < nfox; f += nb - 128) {
;         const int qt = 32 - f / 32, bh = f % 32;
;         fox_item(p, bh * 33 + qt, sm);
.LBB0_412:
	v_readlane_b32 s0, v247, 49
	v_readlane_b32 s1, v247, 50
	s_nop 4
	global_load_dword v8, v9, s[0:1]
	v_readlane_b32 s0, v247, 47
	v_readlane_b32 s1, v247, 48
	s_nop 4
	global_load_dword v10, v9, s[0:1] offset:2048
	s_waitcnt vmcnt(0)
	v_readfirstlane_b32 s48, v8
	v_readfirstlane_b32 s49, v10
	s_cmpk_gt_i32 s48, 0x80
	s_cbranch_scc0 .Lidle_done
	s_mov_b64 s[26:27], 0
	s_branch .Lfx_next

; __device__ __forceinline__ void rwkv_item(const Params& p, int item, float* sm) {
;     ...
;   __syncthreads();
;   RW_LOAD(PADR)
;   RW_STORE(0, PADR)
;   __syncthreads();
;   constexpr int NCH = (LP - PADR) / TC;
;   for (int c = 0; c < NCH; c++) {
;     const int bi = c & 1;
;     const int t0 = PADR + c * TC;
;     if (c + 1 < NCH) RW_LOAD(t0 + TC)
;     {
;       const float* bw = sm + bi * BUF;
;       const float* bv = bw + 5 * TC * 64;
;       float* by = sm + bi * BUF + 5 * TC * 64 + TC * 16 + TC;
;       float yreg[TC];
; #pragma unroll
;       for (int t = 0; t < TC; t++) {
;         const float4 w4 = *(const float4*)(bw + 0 * TC * 64 + t * 64 + sub * 4);
;         const float4 k4 = *(const float4*)(bw + 1 * TC * 64 + t * 64 + sub * 4);
;         const float4 a4 = *(const float4*)(bw + 2 * TC * 64 + t * 64 + sub * 4);
;         const float4 b4 = *(const float4*)(bw + 3 * TC * 64 + t * 64 + sub * 4);
;         const float4 r4 = *(const float4*)(bw + 4 * TC * 64 + t * 64 + sub * 4);
;         const float v = bv[t * 16 + rowl];
.Lrw_nosb_p0:
	s_add_u32 s4, s4, 0x18000
	s_addc_u32 s5, s5, 0
	s_add_u32 s6, s6, 0x8000
	s_addc_u32 s7, s7, 0
	s_add_u32 s8, s8, 0x8000
	s_addc_u32 s9, s9, 0
	s_add_u32 s16, s16, 0x400
	s_addc_u32 s17, s17, 0
	s_mov_b32 s0, 0
	s_mov_b32 s1, 0
	s_waitcnt lgkmcnt(0)
	s_barrier
	v_mov_b32_e32 v10, v47
	v_mov_b32_e32 v11, v136
	s_nop 0
	ds_read_b128 v[56:59], v10 offset:8192
	ds_read_b128 v[48:51], v10
	ds_read_b128 v[52:55], v10 offset:4096
	ds_read_b128 v[60:63], v10 offset:12288
	ds_read_b128 v[80:83], v10 offset:16384
	ds_read_b128 v[88:91], v11 offset:0
	ds_read_b128 v[92:95], v11 offset:16
	ds_read_b128 v[96:99], v11 offset:32
	ds_read_b128 v[100:103], v11 offset:48
	ds_read_b128 v[72:75], v10 offset:8448
	ds_read_b128 v[64:67], v10 offset:256
	ds_read_b128 v[68:71], v10 offset:4352
	ds_read_b128 v[76:79], v10 offset:12544
	ds_read_b128 v[84:87], v10 offset:16640

; __device__ __forceinline__ void rwkv_item(const Params& p, int item, float* sm) {
;     ...
;       for (int t = 0; t < TC; t++) {
;         const float4 w4 = *(const float4*)(bw + 0 * TC * 64 + t * 64 + sub * 4);
;         const float4 k4 = *(const float4*)(bw + 1 * TC * 64 + t * 64 + sub * 4);
;         const float4 a4 = *(const float4*)(bw + 2 * TC * 64 + t * 64 + sub * 4);
;         const float4 b4 = *(const float4*)(bw + 3 * TC * 64 + t * 64 + sub * 4);
;         const float4 r4 = *(const float4*)(bw + 4 * TC * 64 + t * 64 + sub * 4);
;         const float v = bv[t * 16 + rowl];
;         const float sa = dpp_sum16((S0 * a4.x + S1 * a4.y) + (S2 * a4.z + S3 * a4.w));
;         S0 = (S0 * w4.x + v * k4.x) + sa * b4.x;
;         S1 = (S1 * w4.y + v * k4.y) + sa * b4.y;
;         S2 = (S2 * w4.z + v * k4.z) + sa * b4.z;
;         S3 = (S3 * w4.w + v * k4.w) + sa * b4.w;
;         yreg[t] = (S0 * r4.x + S1 * r4.y) + (S2 * r4.z + S3 * r4.w);
;       }
.Lrw_noload:
	s_waitcnt lgkmcnt(5)
	ds_read_b128 v[152:155], v10 offset:8704
	ds_read_b128 v[144:147], v10 offset:512
	v_pk_mul_f32 v[120:121], v[12:13], v[56:57]
	v_pk_fma_f32 v[120:121], v[14:15], v[58:59], v[120:121]
	v_pk_mul_f32 v[122:123], v[12:13], v[48:49]
	v_add_f32_e32 v128, v120, v121
	v_pk_mul_f32 v[124:125], v[14:15], v[50:51]
	v_pk_fma_f32 v[122:123], v[52:53], v[88:89], v[122:123] op_sel_hi:[1,0,1]
	v_add_f32_dpp v128, v128, v128 quad_perm:[1,0,3,2] row_mask:0xf bank_mask:0xf bound_ctrl:1
	v_pk_fma_f32 v[124:125], v[54:55], v[88:89], v[124:125] op_sel_hi:[1,0,1]
	ds_read_b128 v[148:151], v10 offset:4608
	v_add_f32_dpp v128, v128, v128 quad_perm:[2,3,0,1] row_mask:0xf bank_mask:0xf bound_ctrl:1
	ds_read_b128 v[156:159], v10 offset:12800
	ds_read_b128 v[138:141], v10 offset:16896
	v_add_f32_dpp v128, v128, v128 row_half_mirror row_mask:0xf bank_mask:0xf bound_ctrl:1
	s_nop 1
	v_add_f32_dpp v130, v128, v128 row_mirror row_mask:0xf bank_mask:0xf bound_ctrl:1
	v_pk_fma_f32 v[12:13], v[60:61], v[130:131], v[122:123] op_sel_hi:[1,0,1]
	v_pk_fma_f32 v[14:15], v[62:63], v[130:131], v[124:125] op_sel_hi:[1,0,1]
	v_pk_mul_f32 v[126:127], v[12:13], v[80:81]
	v_pk_fma_f32 v[126:127], v[14:15], v[82:83], v[126:127]
	s_waitcnt lgkmcnt(5)
	ds_read_b128 v[56:59], v10 offset:8960
	ds_read_b128 v[48:51], v10 offset:768
	v_pk_mul_f32 v[120:121], v[12:13], v[72:73]
	v_pk_fma_f32 v[120:121], v[14:15], v[74:75], v[120:121]
	v_pk_mul_f32 v[122:123], v[12:13], v[64:65]
	v_add_f32_e32 v128, v120, v121
	v_pk_mul_f32 v[124:125], v[14:15], v[66:67]
	v_pk_fma_f32 v[122:123], v[68:69], v[88:89], v[122:123] op_sel:[0,1,0] op_sel_hi:[1,1,1]
	v_add_f32_dpp v128, v128, v128 quad_perm:[1,0,3,2] row_mask:0xf bank_mask:0xf bound_ctrl:1
	v_pk_fma_f32 v[124:125], v[70:71], v[88:89], v[124:125] op_sel:[0,1,0] op_sel_hi:[1,1,1]
	ds_read_b128 v[52:55], v10 offset:4864
	v_add_f32_dpp v128, v128, v128 quad_perm:[2,3,0,1] row_mask:0xf bank_mask:0xf bound_ctrl:1
	ds_read_b128 v[60:63], v10 offset:13056
	ds_read_b128 v[80:83], v10 offset:17152
	v_add_f32_dpp v128, v128, v128 row_half_mirror row_mask:0xf bank_mask:0xf bound_ctrl:1
	v_add_f32_e32 v104, v126, v127
	s_nop 0
	v_add_f32_dpp v130, v128, v128 row_mirror row_mask:0xf bank_mask:0xf bound_ctrl:1
	v_pk_fma_f32 v[12:13], v[76:77], v[130:131], v[122:123] op_sel_hi:[1,0,1]
	v_pk_fma_f32 v[14:15], v[78:79], v[130:131], v[124:125] op_sel_hi:[1,0,1]
	v_pk_mul_f32 v[126:127], v[12:13], v[84:85]
	v_pk_fma_f32 v[126:127], v[14:15], v[86:87], v[126:127]
	s_waitcnt lgkmcnt(5)
	ds_read_b128 v[72:75], v10 offset:9216
	ds_read_b128 v[64:67], v10 offset:1024
	v_pk_mul_f32 v[120:121], v[12:13], v[152:153]
	v_pk_fma_f32 v[120:121], v[14:15], v[154:155], v[120:121]
	v_pk_mul_f32 v[122:123], v[12:13], v[144:145]
	v_add_f32_e32 v128, v120, v121
	v_pk_mul_f32 v[124:125], v[14:15], v[146:147]
	v_pk_fma_f32 v[122:123], v[148:149], v[90:91], v[122:123] op_sel_hi:[1,0,1]
	v_add_f32_dpp v128, v128, v128 quad_perm:[1,0,3,2] row_mask:0xf bank_mask:0xf bound_ctrl:1
	v_pk_fma_f32 v[124:125], v[150:151], v[90:91], v[124:125] op_sel_hi:[1,0,1]
	ds_read_b128 v[68:71], v10 offset:5120
	v_add_f32_dpp v128, v128, v128 quad_perm:[2,3,0,1] row_mask:0xf bank_mask:0xf bound_ctrl:1
	ds_read_b128 v[76:79], v10 offset:13312
	ds_read_b128 v[84:87], v10 offset:17408
	v_add_f32_dpp v128, v128, v128 row_half_mirror row_mask:0xf bank_mask:0xf bound_ctrl:1
	v_add_f32_e32 v105, v126, v127
	s_nop 0
	v_add_f32_dpp v130, v128, v128 row_mirror row_mask:0xf bank_mask:0xf bound_ctrl:1
	v_pk_fma_f32 v[12:13], v[156:157], v[130:131], v[122:123] op_sel_hi:[1,0,1]
	v_pk_fma_f32 v[14:15], v[158:159], v[130:131], v[124:125] op_sel_hi:[1,0,1]
	v_pk_mul_f32 v[126:127], v[12:13], v[138:139]
	v_pk_fma_f32 v[126:127], v[14:15], v[140:141], v[126:127]
	s_waitcnt lgkmcnt(5)
	ds_read_b128 v[152:155], v10 offset:9472
	ds_read_b128 v[144:147], v10 offset:1280
	v_pk_mul_f32 v[120:121], v[12:13], v[56:57]
	v_pk_fma_f32 v[120:121], v[14:15], v[58:59], v[120:121]
	v_pk_mul_f32 v[122:123], v[12:13], v[48:49]
	v_add_f32_e32 v128, v120, v121
	v_pk_mul_f32 v[124:125], v[14:15], v[50:51]
	v_pk_fma_f32 v[122:123], v[52:53], v[90:91], v[122:123] op_sel:[0,1,0] op_sel_hi:[1,1,1]
	v_add_f32_dpp v128, v128, v128 quad_perm:[1,0,3,2] row_mask:0xf bank_mask:0xf bound_ctrl:1
	v_pk_fma_f32 v[124:125], v[54:55], v[90:91], v[124:125] op_sel:[0,1,0] op_sel_hi:[1,1,1]
	ds_read_b128 v[148:151], v10 offset:5376
	v_add_f32_dpp v128, v128, v128 quad_perm:[2,3,0,1] row_mask:0xf bank_mask:0xf bound_ctrl:1
	ds_read_b128 v[156:159], v10 offset:13568
	ds_read_b128 v[138:141], v10 offset:17664
	v_add_f32_dpp v128, v128, v128 row_half_mirror row_mask:0xf bank_mask:0xf bound_ctrl:1
	v_add_f32_e32 v106, v126, v127
	s_nop 0
	v_add_f32_dpp v130, v128, v128 row_mirror row_mask:0xf bank_mask:0xf bound_ctrl:1
	v_pk_fma_f32 v[12:13], v[60:61], v[130:131], v[122:123] op_sel_hi:[1,0,1]
	v_pk_fma_f32 v[14:15], v[62:63], v[130:131], v[124:125] op_sel_hi:[1,0,1]
	v_pk_mul_f32 v[126:127], v[12:13], v[80:81]
	v_pk_fma_f32 v[126:127], v[14:15], v[82:83], v[126:127]
	s_waitcnt lgkmcnt(5)
; __device__ __forceinline__ void rwkv_item(const Params& p, int item, float* sm) {
;     ...
; #pragma unroll
;       for (int t = 0; t < TC; t++) {
;         const float4 w4 = *(const float4*)(bw + 0 * TC * 64 + t * 64 + sub * 4);
;         const float4 k4 = *(const float4*)(bw + 1 * TC * 64 + t * 64 + sub * 4);
;         const float4 a4 = *(const float4*)(bw + 2 * TC * 64 + t * 64 + sub * 4);
;         const float4 b4 = *(const float4*)(bw + 3 * TC * 64 + t * 64 + sub * 4);
;         const float4 r4 = *(const float4*)(bw + 4 * TC * 64 + t * 64 + sub * 4);
;         const float v = bv[t * 16 + rowl];
;         const float sa = dpp_sum16((S0 * a4.x + S1 * a4.y) + (S2 * a4.z + S3 * a4.w));
;         S0 = (S0 * w4.x + v * k4.x) + sa * b4.x;
;         S1 = (S1 * w4.y + v * k4.y) + sa * b4.y;
;         S2 = (S2 * w4.z + v * k4.z) + sa * b4.z;
;         S3 = (S3 * w4.w + v * k4.w) + sa * b4.w;
;         yreg[t] = (S0 * r4.x + S1 * r4.y) + (S2 * r4.z + S3 * r4.w);
;       }
	ds_read_b128 v[56:59], v10 offset:9728
	ds_read_b128 v[48:51], v10 offset:1536
	v_pk_mul_f32 v[120:121], v[12:13], v[72:73]
	v_pk_fma_f32 v[120:121], v[14:15], v[74:75], v[120:121]
	v_pk_mul_f32 v[122:123], v[12:13], v[64:65]
	v_add_f32_e32 v128, v120, v121
	v_pk_mul_f32 v[124:125], v[14:15], v[66:67]
	v_pk_fma_f32 v[122:123], v[68:69], v[92:93], v[122:123] op_sel_hi:[1,0,1]
	v_add_f32_dpp v128, v128, v128 quad_perm:[1,0,3,2] row_mask:0xf bank_mask:0xf bound_ctrl:1
	v_pk_fma_f32 v[124:125], v[70:71], v[92:93], v[124:125] op_sel_hi:[1,0,1]
	ds_read_b128 v[52:55], v10 offset:5632
	v_add_f32_dpp v128, v128, v128 quad_perm:[2,3,0,1] row_mask:0xf bank_mask:0xf bound_ctrl:1
	ds_read_b128 v[60:63], v10 offset:13824
	ds_read_b128 v[80:83], v10 offset:17920
	v_add_f32_dpp v128, v128, v128 row_half_mirror row_mask:0xf bank_mask:0xf bound_ctrl:1
	v_add_f32_e32 v107, v126, v127
	s_nop 0
	v_add_f32_dpp v130, v128, v128 row_mirror row_mask:0xf bank_mask:0xf bound_ctrl:1
	v_pk_fma_f32 v[12:13], v[76:77], v[130:131], v[122:123] op_sel_hi:[1,0,1]
	v_pk_fma_f32 v[14:15], v[78:79], v[130:131], v[124:125] op_sel_hi:[1,0,1]
	v_pk_mul_f32 v[126:127], v[12:13], v[84:85]
	v_pk_fma_f32 v[126:127], v[14:15], v[86:87], v[126:127]
	s_waitcnt lgkmcnt(5)
	ds_read_b128 v[72:75], v10 offset:9984
	ds_read_b128 v[64:67], v10 offset:1792
	v_pk_mul_f32 v[120:121], v[12:13], v[152:153]
	v_pk_fma_f32 v[120:121], v[14:15], v[154:155], v[120:121]
	v_pk_mul_f32 v[122:123], v[12:13], v[144:145]
	v_add_f32_e32 v128, v120, v121
	v_pk_mul_f32 v[124:125], v[14:15], v[146:147]
	v_pk_fma_f32 v[122:123], v[148:149], v[92:93], v[122:123] op_sel:[0,1,0] op_sel_hi:[1,1,1]
	v_add_f32_dpp v128, v128, v128 quad_perm:[1,0,3,2] row_mask:0xf bank_mask:0xf bound_ctrl:1
	v_pk_fma_f32 v[124:125], v[150:151], v[92:93], v[124:125] op_sel:[0,1,0] op_sel_hi:[1,1,1]
	ds_read_b128 v[68:71], v10 offset:5888
	v_add_f32_dpp v128, v128, v128 quad_perm:[2,3,0,1] row_mask:0xf bank_mask:0xf bound_ctrl:1
	ds_read_b128 v[76:79], v10 offset:14080
	ds_read_b128 v[84:87], v10 offset:18176
	v_add_f32_dpp v128, v128, v128 row_half_mirror row_mask:0xf bank_mask:0xf bound_ctrl:1
	v_add_f32_e32 v108, v126, v127
	s_nop 0
	v_add_f32_dpp v130, v128, v128 row_mirror row_mask:0xf bank_mask:0xf bound_ctrl:1
	v_pk_fma_f32 v[12:13], v[156:157], v[130:131], v[122:123] op_sel_hi:[1,0,1]
	v_pk_fma_f32 v[14:15], v[158:159], v[130:131], v[124:125] op_sel_hi:[1,0,1]
	v_pk_mul_f32 v[126:127], v[12:13], v[138:139]
	v_pk_fma_f32 v[126:127], v[14:15], v[140:141], v[126:127]
	s_waitcnt lgkmcnt(5)
	ds_read_b128 v[152:155], v10 offset:10240
	ds_read_b128 v[144:147], v10 offset:2048
	v_pk_mul_f32 v[120:121], v[12:13], v[56:57]
	v_pk_fma_f32 v[120:121], v[14:15], v[58:59], v[120:121]
	v_pk_mul_f32 v[122:123], v[12:13], v[48:49]
	v_add_f32_e32 v128, v120, v121
	v_pk_mul_f32 v[124:125], v[14:15], v[50:51]
	v_pk_fma_f32 v[122:123], v[52:53], v[94:95], v[122:123] op_sel_hi:[1,0,1]
	v_add_f32_dpp v128, v128, v128 quad_perm:[1,0,3,2] row_mask:0xf bank_mask:0xf bound_ctrl:1
	v_pk_fma_f32 v[124:125], v[54:55], v[94:95], v[124:125] op_sel_hi:[1,0,1]
	ds_read_b128 v[148:151], v10 offset:6144
	v_add_f32_dpp v128, v128, v128 quad_perm:[2,3,0,1] row_mask:0xf bank_mask:0xf bound_ctrl:1
	ds_read_b128 v[156:159], v10 offset:14336
	ds_read_b128 v[138:141], v10 offset:18432
	v_add_f32_dpp v128, v128, v128 row_half_mirror row_mask:0xf bank_mask:0xf bound_ctrl:1
	v_add_f32_e32 v109, v126, v127
	s_nop 0
	v_add_f32_dpp v130, v128, v128 row_mirror row_mask:0xf bank_mask:0xf bound_ctrl:1
	v_pk_fma_f32 v[12:13], v[60:61], v[130:131], v[122:123] op_sel_hi:[1,0,1]
	v_pk_fma_f32 v[14:15], v[62:63], v[130:131], v[124:125] op_sel_hi:[1,0,1]
	v_pk_mul_f32 v[126:127], v[12:13], v[80:81]
	v_pk_fma_f32 v[126:127], v[14:15], v[82:83], v[126:127]
	s_waitcnt lgkmcnt(5)
	ds_read_b128 v[56:59], v10 offset:10496
	ds_read_b128 v[48:51], v10 offset:2304
	v_pk_mul_f32 v[120:121], v[12:13], v[72:73]
	v_pk_fma_f32 v[120:121], v[14:15], v[74:75], v[120:121]
	v_pk_mul_f32 v[122:123], v[12:13], v[64:65]
	v_add_f32_e32 v128, v120, v121
	v_pk_mul_f32 v[124:125], v[14:15], v[66:67]
	v_pk_fma_f32 v[122:123], v[68:69], v[94:95], v[122:123] op_sel:[0,1,0] op_sel_hi:[1,1,1]
	v_add_f32_dpp v128, v128, v128 quad_perm:[1,0,3,2] row_mask:0xf bank_mask:0xf bound_ctrl:1
	v_pk_fma_f32 v[124:125], v[70:71], v[94:95], v[124:125] op_sel:[0,1,0] op_sel_hi:[1,1,1]
	ds_read_b128 v[52:55], v10 offset:6400
	v_add_f32_dpp v128, v128, v128 quad_perm:[2,3,0,1] row_mask:0xf bank_mask:0xf bound_ctrl:1
	ds_read_b128 v[60:63], v10 offset:14592
	ds_read_b128 v[80:83], v10 offset:18688
	v_add_f32_dpp v128, v128, v128 row_half_mirror row_mask:0xf bank_mask:0xf bound_ctrl:1
	v_add_f32_e32 v110, v126, v127
	s_nop 0
	v_add_f32_dpp v130, v128, v128 row_mirror row_mask:0xf bank_mask:0xf bound_ctrl:1
	v_pk_fma_f32 v[12:13], v[76:77], v[130:131], v[122:123] op_sel_hi:[1,0,1]
	v_pk_fma_f32 v[14:15], v[78:79], v[130:131], v[124:125] op_sel_hi:[1,0,1]
	v_pk_mul_f32 v[126:127], v[12:13], v[84:85]
	v_pk_fma_f32 v[126:127], v[14:15], v[86:87], v[126:127]
	s_waitcnt lgkmcnt(5)
; __device__ __forceinline__ void rwkv_item(const Params& p, int item, float* sm) {
;     ...
; #pragma unroll
;       for (int t = 0; t < TC; t++) {
;         const float4 w4 = *(const float4*)(bw + 0 * TC * 64 + t * 64 + sub * 4);
;         const float4 k4 = *(const float4*)(bw + 1 * TC * 64 + t * 64 + sub * 4);
;         const float4 a4 = *(const float4*)(bw + 2 * TC * 64 + t * 64 + sub * 4);
;         const float4 b4 = *(const float4*)(bw + 3 * TC * 64 + t * 64 + sub * 4);
;         const float4 r4 = *(const float4*)(bw + 4 * TC * 64 + t * 64 + sub * 4);
;         const float v = bv[t * 16 + rowl];
;         const float sa = dpp_sum16((S0 * a4.x + S1 * a4.y) + (S2 * a4.z + S3 * a4.w));
;         S0 = (S0 * w4.x + v * k4.x) + sa * b4.x;
;         S1 = (S1 * w4.y + v * k4.y) + sa * b4.y;
;         S2 = (S2 * w4.z + v * k4.z) + sa * b4.z;
;         S3 = (S3 * w4.w + v * k4.w) + sa * b4.w;
;         yreg[t] = (S0 * r4.x + S1 * r4.y) + (S2 * r4.z + S3 * r4.w);
;       }
	ds_read_b128 v[72:75], v10 offset:10752
	ds_read_b128 v[64:67], v10 offset:2560
	v_pk_mul_f32 v[120:121], v[12:13], v[152:153]
	v_pk_fma_f32 v[120:121], v[14:15], v[154:155], v[120:121]
	v_pk_mul_f32 v[122:123], v[12:13], v[144:145]
	v_add_f32_e32 v128, v120, v121
	v_pk_mul_f32 v[124:125], v[14:15], v[146:147]
	v_pk_fma_f32 v[122:123], v[148:149], v[96:97], v[122:123] op_sel_hi:[1,0,1]
	v_add_f32_dpp v128, v128, v128 quad_perm:[1,0,3,2] row_mask:0xf bank_mask:0xf bound_ctrl:1
	v_pk_fma_f32 v[124:125], v[150:151], v[96:97], v[124:125] op_sel_hi:[1,0,1]
	ds_read_b128 v[68:71], v10 offset:6656
	v_add_f32_dpp v128, v128, v128 quad_perm:[2,3,0,1] row_mask:0xf bank_mask:0xf bound_ctrl:1
	ds_read_b128 v[76:79], v10 offset:14848
	ds_read_b128 v[84:87], v10 offset:18944
	v_add_f32_dpp v128, v128, v128 row_half_mirror row_mask:0xf bank_mask:0xf bound_ctrl:1
	v_add_f32_e32 v111, v126, v127
	s_nop 0
	v_add_f32_dpp v130, v128, v128 row_mirror row_mask:0xf bank_mask:0xf bound_ctrl:1
	v_pk_fma_f32 v[12:13], v[156:157], v[130:131], v[122:123] op_sel_hi:[1,0,1]
	v_pk_fma_f32 v[14:15], v[158:159], v[130:131], v[124:125] op_sel_hi:[1,0,1]
	v_pk_mul_f32 v[126:127], v[12:13], v[138:139]
	v_pk_fma_f32 v[126:127], v[14:15], v[140:141], v[126:127]
	s_waitcnt lgkmcnt(5)
	ds_read_b128 v[152:155], v10 offset:11008
	ds_read_b128 v[144:147], v10 offset:2816
	v_pk_mul_f32 v[120:121], v[12:13], v[56:57]
	v_pk_fma_f32 v[120:121], v[14:15], v[58:59], v[120:121]
	v_pk_mul_f32 v[122:123], v[12:13], v[48:49]
	v_add_f32_e32 v128, v120, v121
	v_pk_mul_f32 v[124:125], v[14:15], v[50:51]
	v_pk_fma_f32 v[122:123], v[52:53], v[96:97], v[122:123] op_sel:[0,1,0] op_sel_hi:[1,1,1]
	v_add_f32_dpp v128, v128, v128 quad_perm:[1,0,3,2] row_mask:0xf bank_mask:0xf bound_ctrl:1
	v_pk_fma_f32 v[124:125], v[54:55], v[96:97], v[124:125] op_sel:[0,1,0] op_sel_hi:[1,1,1]
	ds_read_b128 v[148:151], v10 offset:6912
	v_add_f32_dpp v128, v128, v128 quad_perm:[2,3,0,1] row_mask:0xf bank_mask:0xf bound_ctrl:1
	ds_read_b128 v[156:159], v10 offset:15104
	ds_read_b128 v[138:141], v10 offset:19200
	v_add_f32_dpp v128, v128, v128 row_half_mirror row_mask:0xf bank_mask:0xf bound_ctrl:1
	v_add_f32_e32 v112, v126, v127
	s_nop 0
	v_add_f32_dpp v130, v128, v128 row_mirror row_mask:0xf bank_mask:0xf bound_ctrl:1
	v_pk_fma_f32 v[12:13], v[60:61], v[130:131], v[122:123] op_sel_hi:[1,0,1]
	v_pk_fma_f32 v[14:15], v[62:63], v[130:131], v[124:125] op_sel_hi:[1,0,1]
	v_pk_mul_f32 v[126:127], v[12:13], v[80:81]
	v_pk_fma_f32 v[126:127], v[14:15], v[82:83], v[126:127]
	s_waitcnt lgkmcnt(5)
	ds_read_b128 v[56:59], v10 offset:11264
	ds_read_b128 v[48:51], v10 offset:3072
	v_pk_mul_f32 v[120:121], v[12:13], v[72:73]
	v_pk_fma_f32 v[120:121], v[14:15], v[74:75], v[120:121]
	v_pk_mul_f32 v[122:123], v[12:13], v[64:65]
	v_add_f32_e32 v128, v120, v121
	v_pk_mul_f32 v[124:125], v[14:15], v[66:67]
	v_pk_fma_f32 v[122:123], v[68:69], v[98:99], v[122:123] op_sel_hi:[1,0,1]
	v_add_f32_dpp v128, v128, v128 quad_perm:[1,0,3,2] row_mask:0xf bank_mask:0xf bound_ctrl:1
	v_pk_fma_f32 v[124:125], v[70:71], v[98:99], v[124:125] op_sel_hi:[1,0,1]
	ds_read_b128 v[52:55], v10 offset:7168
	v_add_f32_dpp v128, v128, v128 quad_perm:[2,3,0,1] row_mask:0xf bank_mask:0xf bound_ctrl:1
	ds_read_b128 v[60:63], v10 offset:15360
	ds_read_b128 v[80:83], v10 offset:19456
	v_add_f32_dpp v128, v128, v128 row_half_mirror row_mask:0xf bank_mask:0xf bound_ctrl:1
	v_add_f32_e32 v113, v126, v127
	s_nop 0
	v_add_f32_dpp v130, v128, v128 row_mirror row_mask:0xf bank_mask:0xf bound_ctrl:1
	v_pk_fma_f32 v[12:13], v[76:77], v[130:131], v[122:123] op_sel_hi:[1,0,1]
	v_pk_fma_f32 v[14:15], v[78:79], v[130:131], v[124:125] op_sel_hi:[1,0,1]
	v_pk_mul_f32 v[126:127], v[12:13], v[84:85]
	v_pk_fma_f32 v[126:127], v[14:15], v[86:87], v[126:127]
	s_waitcnt lgkmcnt(5)
	ds_read_b128 v[72:75], v10 offset:11520
	ds_read_b128 v[64:67], v10 offset:3328
	v_pk_mul_f32 v[120:121], v[12:13], v[152:153]
	v_pk_fma_f32 v[120:121], v[14:15], v[154:155], v[120:121]
	v_pk_mul_f32 v[122:123], v[12:13], v[144:145]
	v_add_f32_e32 v128, v120, v121
	v_pk_mul_f32 v[124:125], v[14:15], v[146:147]
	v_pk_fma_f32 v[122:123], v[148:149], v[98:99], v[122:123] op_sel:[0,1,0] op_sel_hi:[1,1,1]
	v_add_f32_dpp v128, v128, v128 quad_perm:[1,0,3,2] row_mask:0xf bank_mask:0xf bound_ctrl:1
	v_pk_fma_f32 v[124:125], v[150:151], v[98:99], v[124:125] op_sel:[0,1,0] op_sel_hi:[1,1,1]
	ds_read_b128 v[68:71], v10 offset:7424
	v_add_f32_dpp v128, v128, v128 quad_perm:[2,3,0,1] row_mask:0xf bank_mask:0xf bound_ctrl:1
	ds_read_b128 v[76:79], v10 offset:15616
	ds_read_b128 v[84:87], v10 offset:19712
	v_add_f32_dpp v128, v128, v128 row_half_mirror row_mask:0xf bank_mask:0xf bound_ctrl:1
	v_add_f32_e32 v114, v126, v127
	s_nop 0
	v_add_f32_dpp v130, v128, v128 row_mirror row_mask:0xf bank_mask:0xf bound_ctrl:1
	v_pk_fma_f32 v[12:13], v[156:157], v[130:131], v[122:123] op_sel_hi:[1,0,1]
	v_pk_fma_f32 v[14:15], v[158:159], v[130:131], v[124:125] op_sel_hi:[1,0,1]
	v_pk_mul_f32 v[126:127], v[12:13], v[138:139]
	v_pk_fma_f32 v[126:127], v[14:15], v[140:141], v[126:127]
	s_waitcnt lgkmcnt(5)
; __device__ __forceinline__ void rwkv_item(const Params& p, int item, float* sm) {
;     ...
; #pragma unroll
;       for (int t = 0; t < TC; t++) {
;         const float4 w4 = *(const float4*)(bw + 0 * TC * 64 + t * 64 + sub * 4);
;         const float4 k4 = *(const float4*)(bw + 1 * TC * 64 + t * 64 + sub * 4);
;         const float4 a4 = *(const float4*)(bw + 2 * TC * 64 + t * 64 + sub * 4);
;         const float4 b4 = *(const float4*)(bw + 3 * TC * 64 + t * 64 + sub * 4);
;         const float4 r4 = *(const float4*)(bw + 4 * TC * 64 + t * 64 + sub * 4);
;         const float v = bv[t * 16 + rowl];
;         const float sa = dpp_sum16((S0 * a4.x + S1 * a4.y) + (S2 * a4.z + S3 * a4.w));
;         S0 = (S0 * w4.x + v * k4.x) + sa * b4.x;
;         S1 = (S1 * w4.y + v * k4.y) + sa * b4.y;
;         S2 = (S2 * w4.z + v * k4.z) + sa * b4.z;
;         S3 = (S3 * w4.w + v * k4.w) + sa * b4.w;
;         yreg[t] = (S0 * r4.x + S1 * r4.y) + (S2 * r4.z + S3 * r4.w);
;       }
; #pragma unroll
;       for (int t = 0; t < TC; t++) yreg[t] = dpp_sum16(yreg[t]);
	ds_read_b128 v[152:155], v10 offset:11776
	ds_read_b128 v[144:147], v10 offset:3584
	v_pk_mul_f32 v[120:121], v[12:13], v[56:57]
	v_pk_fma_f32 v[120:121], v[14:15], v[58:59], v[120:121]
	v_pk_mul_f32 v[122:123], v[12:13], v[48:49]
	v_add_f32_e32 v128, v120, v121
	v_pk_mul_f32 v[124:125], v[14:15], v[50:51]
	v_pk_fma_f32 v[122:123], v[52:53], v[100:101], v[122:123] op_sel_hi:[1,0,1]
	v_add_f32_dpp v128, v128, v128 quad_perm:[1,0,3,2] row_mask:0xf bank_mask:0xf bound_ctrl:1
	v_pk_fma_f32 v[124:125], v[54:55], v[100:101], v[124:125] op_sel_hi:[1,0,1]
	ds_read_b128 v[148:151], v10 offset:7680
	v_add_f32_dpp v128, v128, v128 quad_perm:[2,3,0,1] row_mask:0xf bank_mask:0xf bound_ctrl:1
	ds_read_b128 v[156:159], v10 offset:15872
	ds_read_b128 v[138:141], v10 offset:19968
	v_add_f32_dpp v128, v128, v128 row_half_mirror row_mask:0xf bank_mask:0xf bound_ctrl:1
	v_add_f32_e32 v115, v126, v127
	s_nop 0
	v_add_f32_dpp v130, v128, v128 row_mirror row_mask:0xf bank_mask:0xf bound_ctrl:1
	v_pk_fma_f32 v[12:13], v[60:61], v[130:131], v[122:123] op_sel_hi:[1,0,1]
	v_pk_fma_f32 v[14:15], v[62:63], v[130:131], v[124:125] op_sel_hi:[1,0,1]
	v_pk_mul_f32 v[126:127], v[12:13], v[80:81]
	v_pk_fma_f32 v[126:127], v[14:15], v[82:83], v[126:127]
	s_waitcnt lgkmcnt(5)
	ds_read_b128 v[56:59], v10 offset:12032
	ds_read_b128 v[48:51], v10 offset:3840
	v_pk_mul_f32 v[120:121], v[12:13], v[72:73]
	v_pk_fma_f32 v[120:121], v[14:15], v[74:75], v[120:121]
	v_pk_mul_f32 v[122:123], v[12:13], v[64:65]
	v_add_f32_e32 v128, v120, v121
	v_pk_mul_f32 v[124:125], v[14:15], v[66:67]
	v_pk_fma_f32 v[122:123], v[68:69], v[100:101], v[122:123] op_sel:[0,1,0] op_sel_hi:[1,1,1]
	v_add_f32_dpp v128, v128, v128 quad_perm:[1,0,3,2] row_mask:0xf bank_mask:0xf bound_ctrl:1
	v_pk_fma_f32 v[124:125], v[70:71], v[100:101], v[124:125] op_sel:[0,1,0] op_sel_hi:[1,1,1]
	ds_read_b128 v[52:55], v10 offset:7936
	v_add_f32_dpp v128, v128, v128 quad_perm:[2,3,0,1] row_mask:0xf bank_mask:0xf bound_ctrl:1
	ds_read_b128 v[60:63], v10 offset:16128
	ds_read_b128 v[80:83], v10 offset:20224
	v_add_f32_dpp v128, v128, v128 row_half_mirror row_mask:0xf bank_mask:0xf bound_ctrl:1
	v_add_f32_e32 v116, v126, v127
	s_nop 0
	v_add_f32_dpp v130, v128, v128 row_mirror row_mask:0xf bank_mask:0xf bound_ctrl:1
	v_pk_fma_f32 v[12:13], v[76:77], v[130:131], v[122:123] op_sel_hi:[1,0,1]
	v_pk_fma_f32 v[14:15], v[78:79], v[130:131], v[124:125] op_sel_hi:[1,0,1]
	v_pk_mul_f32 v[126:127], v[12:13], v[84:85]
	v_pk_fma_f32 v[126:127], v[14:15], v[86:87], v[126:127]
	s_waitcnt lgkmcnt(5)
	v_pk_mul_f32 v[120:121], v[12:13], v[152:153]
	v_pk_fma_f32 v[120:121], v[14:15], v[154:155], v[120:121]
	v_pk_mul_f32 v[122:123], v[12:13], v[144:145]
	v_add_f32_e32 v128, v120, v121
	v_pk_mul_f32 v[124:125], v[14:15], v[146:147]
	v_pk_fma_f32 v[122:123], v[148:149], v[102:103], v[122:123] op_sel_hi:[1,0,1]
	v_add_f32_dpp v128, v128, v128 quad_perm:[1,0,3,2] row_mask:0xf bank_mask:0xf bound_ctrl:1
	v_pk_fma_f32 v[124:125], v[150:151], v[102:103], v[124:125] op_sel_hi:[1,0,1]
	s_nop 0
	v_add_f32_dpp v128, v128, v128 quad_perm:[2,3,0,1] row_mask:0xf bank_mask:0xf bound_ctrl:1
	s_nop 1
	v_add_f32_dpp v128, v128, v128 row_half_mirror row_mask:0xf bank_mask:0xf bound_ctrl:1
	v_add_f32_e32 v117, v126, v127
	s_nop 0
	v_add_f32_dpp v130, v128, v128 row_mirror row_mask:0xf bank_mask:0xf bound_ctrl:1
	v_pk_fma_f32 v[12:13], v[156:157], v[130:131], v[122:123] op_sel_hi:[1,0,1]
	v_pk_fma_f32 v[14:15], v[158:159], v[130:131], v[124:125] op_sel_hi:[1,0,1]
	v_pk_mul_f32 v[126:127], v[12:13], v[138:139]
	v_pk_fma_f32 v[126:127], v[14:15], v[140:141], v[126:127]
	s_waitcnt lgkmcnt(0)
	v_pk_mul_f32 v[120:121], v[12:13], v[56:57]
	v_pk_fma_f32 v[120:121], v[14:15], v[58:59], v[120:121]
	v_pk_mul_f32 v[122:123], v[12:13], v[48:49]
	v_add_f32_e32 v128, v120, v121
	v_pk_mul_f32 v[124:125], v[14:15], v[50:51]
	v_pk_fma_f32 v[122:123], v[52:53], v[102:103], v[122:123] op_sel:[0,1,0] op_sel_hi:[1,1,1]
	v_add_f32_dpp v128, v128, v128 quad_perm:[1,0,3,2] row_mask:0xf bank_mask:0xf bound_ctrl:1
	v_pk_fma_f32 v[124:125], v[54:55], v[102:103], v[124:125] op_sel:[0,1,0] op_sel_hi:[1,1,1]
	s_nop 0
	v_add_f32_dpp v128, v128, v128 quad_perm:[2,3,0,1] row_mask:0xf bank_mask:0xf bound_ctrl:1
	s_nop 1
	v_add_f32_dpp v128, v128, v128 row_half_mirror row_mask:0xf bank_mask:0xf bound_ctrl:1
	v_add_f32_e32 v118, v126, v127
	s_nop 0
	v_add_f32_dpp v130, v128, v128 row_mirror row_mask:0xf bank_mask:0xf bound_ctrl:1
	v_pk_fma_f32 v[12:13], v[60:61], v[130:131], v[122:123] op_sel_hi:[1,0,1]
	v_pk_fma_f32 v[14:15], v[62:63], v[130:131], v[124:125] op_sel_hi:[1,0,1]
	v_pk_mul_f32 v[126:127], v[12:13], v[80:81]
	v_pk_fma_f32 v[126:127], v[14:15], v[82:83], v[126:127]
	v_add_f32_e32 v119, v126, v127
	v_add_f32_dpp v104, v104, v104 quad_perm:[1,0,3,2] row_mask:0xf bank_mask:0xf bound_ctrl:1
	v_add_f32_dpp v105, v105, v105 quad_perm:[1,0,3,2] row_mask:0xf bank_mask:0xf bound_ctrl:1
	v_add_f32_dpp v106, v106, v106 quad_perm:[1,0,3,2] row_mask:0xf bank_mask:0xf bound_ctrl:1
	v_add_f32_dpp v107, v107, v107 quad_perm:[1,0,3,2] row_mask:0xf bank_mask:0xf bound_ctrl:1
	v_add_f32_dpp v108, v108, v108 quad_perm:[1,0,3,2] row_mask:0xf bank_mask:0xf bound_ctrl:1
	v_add_f32_dpp v109, v109, v109 quad_perm:[1,0,3,2] row_mask:0xf bank_mask:0xf bound_ctrl:1
	v_add_f32_dpp v110, v110, v110 quad_perm:[1,0,3,2] row_mask:0xf bank_mask:0xf bound_ctrl:1
	v_add_f32_dpp v111, v111, v111 quad_perm:[1,0,3,2] row_mask:0xf bank_mask:0xf bound_ctrl:1
	v_add_f32_dpp v112, v112, v112 quad_perm:[1,0,3,2] row_mask:0xf bank_mask:0xf bound_ctrl:1
	v_add_f32_dpp v113, v113, v113 quad_perm:[1,0,3,2] row_mask:0xf bank_mask:0xf bound_ctrl:1
; __device__ __forceinline__ void rwkv_item(const Params& p, int item, float* sm) {
;     ...
; #pragma unroll
;       for (int t = 0; t < TC; t++) yreg[t] = dpp_sum16(yreg[t]);
;       if (sub == 0) {
; #pragma unroll
;         for (int t = 0; t < TC; t++) by[t * 16 + rowl] = yreg[t];
;       }
;     }
;     if (c + 1 < NCH) RW_STORE(bi ^ 1, t0 + TC)
	v_add_f32_dpp v114, v114, v114 quad_perm:[1,0,3,2] row_mask:0xf bank_mask:0xf bound_ctrl:1
	v_add_f32_dpp v115, v115, v115 quad_perm:[1,0,3,2] row_mask:0xf bank_mask:0xf bound_ctrl:1
	v_add_f32_dpp v116, v116, v116 quad_perm:[1,0,3,2] row_mask:0xf bank_mask:0xf bound_ctrl:1
	v_add_f32_dpp v117, v117, v117 quad_perm:[1,0,3,2] row_mask:0xf bank_mask:0xf bound_ctrl:1
	v_add_f32_dpp v118, v118, v118 quad_perm:[1,0,3,2] row_mask:0xf bank_mask:0xf bound_ctrl:1
	v_add_f32_dpp v119, v119, v119 quad_perm:[1,0,3,2] row_mask:0xf bank_mask:0xf bound_ctrl:1
	v_add_f32_dpp v104, v104, v104 quad_perm:[2,3,0,1] row_mask:0xf bank_mask:0xf bound_ctrl:1
	v_add_f32_dpp v105, v105, v105 quad_perm:[2,3,0,1] row_mask:0xf bank_mask:0xf bound_ctrl:1
	v_add_f32_dpp v106, v106, v106 quad_perm:[2,3,0,1] row_mask:0xf bank_mask:0xf bound_ctrl:1
	v_add_f32_dpp v107, v107, v107 quad_perm:[2,3,0,1] row_mask:0xf bank_mask:0xf bound_ctrl:1
	v_add_f32_dpp v108, v108, v108 quad_perm:[2,3,0,1] row_mask:0xf bank_mask:0xf bound_ctrl:1
	v_add_f32_dpp v109, v109, v109 quad_perm:[2,3,0,1] row_mask:0xf bank_mask:0xf bound_ctrl:1
	v_add_f32_dpp v110, v110, v110 quad_perm:[2,3,0,1] row_mask:0xf bank_mask:0xf bound_ctrl:1
	v_add_f32_dpp v111, v111, v111 quad_perm:[2,3,0,1] row_mask:0xf bank_mask:0xf bound_ctrl:1
	v_add_f32_dpp v112, v112, v112 quad_perm:[2,3,0,1] row_mask:0xf bank_mask:0xf bound_ctrl:1
	v_add_f32_dpp v113, v113, v113 quad_perm:[2,3,0,1] row_mask:0xf bank_mask:0xf bound_ctrl:1
	v_add_f32_dpp v114, v114, v114 quad_perm:[2,3,0,1] row_mask:0xf bank_mask:0xf bound_ctrl:1
	v_add_f32_dpp v115, v115, v115 quad_perm:[2,3,0,1] row_mask:0xf bank_mask:0xf bound_ctrl:1
	v_add_f32_dpp v116, v116, v116 quad_perm:[2,3,0,1] row_mask:0xf bank_mask:0xf bound_ctrl:1
	v_add_f32_dpp v117, v117, v117 quad_perm:[2,3,0,1] row_mask:0xf bank_mask:0xf bound_ctrl:1
	v_add_f32_dpp v118, v118, v118 quad_perm:[2,3,0,1] row_mask:0xf bank_mask:0xf bound_ctrl:1
	v_add_f32_dpp v119, v119, v119 quad_perm:[2,3,0,1] row_mask:0xf bank_mask:0xf bound_ctrl:1
	v_add_f32_dpp v104, v104, v104 row_half_mirror row_mask:0xf bank_mask:0xf bound_ctrl:1
	v_add_f32_dpp v105, v105, v105 row_half_mirror row_mask:0xf bank_mask:0xf bound_ctrl:1
	v_add_f32_dpp v106, v106, v106 row_half_mirror row_mask:0xf bank_mask:0xf bound_ctrl:1
	v_add_f32_dpp v107, v107, v107 row_half_mirror row_mask:0xf bank_mask:0xf bound_ctrl:1
	v_add_f32_dpp v108, v108, v108 row_half_mirror row_mask:0xf bank_mask:0xf bound_ctrl:1
	v_add_f32_dpp v109, v109, v109 row_half_mirror row_mask:0xf bank_mask:0xf bound_ctrl:1
	v_add_f32_dpp v110, v110, v110 row_half_mirror row_mask:0xf bank_mask:0xf bound_ctrl:1
	v_add_f32_dpp v111, v111, v111 row_half_mirror row_mask:0xf bank_mask:0xf bound_ctrl:1
	v_add_f32_dpp v112, v112, v112 row_half_mirror row_mask:0xf bank_mask:0xf bound_ctrl:1
	v_add_f32_dpp v113, v113, v113 row_half_mirror row_mask:0xf bank_mask:0xf bound_ctrl:1
	v_add_f32_dpp v114, v114, v114 row_half_mirror row_mask:0xf bank_mask:0xf bound_ctrl:1
	v_add_f32_dpp v115, v115, v115 row_half_mirror row_mask:0xf bank_mask:0xf bound_ctrl:1
	v_add_f32_dpp v116, v116, v116 row_half_mirror row_mask:0xf bank_mask:0xf bound_ctrl:1
	v_add_f32_dpp v117, v117, v117 row_half_mirror row_mask:0xf bank_mask:0xf bound_ctrl:1
	v_add_f32_dpp v118, v118, v118 row_half_mirror row_mask:0xf bank_mask:0xf bound_ctrl:1
	v_add_f32_dpp v119, v119, v119 row_half_mirror row_mask:0xf bank_mask:0xf bound_ctrl:1
	v_add_f32_dpp v104, v104, v104 row_mirror row_mask:0xf bank_mask:0xf bound_ctrl:1
	v_add_f32_dpp v105, v105, v105 row_mirror row_mask:0xf bank_mask:0xf bound_ctrl:1
	v_add_f32_dpp v106, v106, v106 row_mirror row_mask:0xf bank_mask:0xf bound_ctrl:1
	v_add_f32_dpp v107, v107, v107 row_mirror row_mask:0xf bank_mask:0xf bound_ctrl:1
	v_add_f32_dpp v108, v108, v108 row_mirror row_mask:0xf bank_mask:0xf bound_ctrl:1
	v_add_f32_dpp v109, v109, v109 row_mirror row_mask:0xf bank_mask:0xf bound_ctrl:1
	v_add_f32_dpp v110, v110, v110 row_mirror row_mask:0xf bank_mask:0xf bound_ctrl:1
	v_add_f32_dpp v111, v111, v111 row_mirror row_mask:0xf bank_mask:0xf bound_ctrl:1
	v_add_f32_dpp v112, v112, v112 row_mirror row_mask:0xf bank_mask:0xf bound_ctrl:1
	v_add_f32_dpp v113, v113, v113 row_mirror row_mask:0xf bank_mask:0xf bound_ctrl:1
	v_add_f32_dpp v114, v114, v114 row_mirror row_mask:0xf bank_mask:0xf bound_ctrl:1
	v_add_f32_dpp v115, v115, v115 row_mirror row_mask:0xf bank_mask:0xf bound_ctrl:1
	v_add_f32_dpp v116, v116, v116 row_mirror row_mask:0xf bank_mask:0xf bound_ctrl:1
	v_add_f32_dpp v117, v117, v117 row_mirror row_mask:0xf bank_mask:0xf bound_ctrl:1
	v_add_f32_dpp v118, v118, v118 row_mirror row_mask:0xf bank_mask:0xf bound_ctrl:1
	v_add_f32_dpp v119, v119, v119 row_mirror row_mask:0xf bank_mask:0xf bound_ctrl:1
	v_add_u32_e32 v45, s1, v134
	s_xor_b32 s29, s1, 0x5800
	v_add_u32_e32 v43, s29, v132
	v_add_u32_e32 v44, s29, v133
	ds_write2_b32 v45, v104, v105 offset0:0 offset1:16
	ds_write2_b32 v45, v106, v107 offset0:32 offset1:48
	ds_write2_b32 v45, v108, v109 offset0:64 offset1:80
	ds_write2_b32 v45, v110, v111 offset0:96 offset1:112
	ds_write2_b32 v45, v112, v113 offset0:128 offset1:144
	ds_write2_b32 v45, v114, v115 offset0:160 offset1:176
	ds_write2_b32 v45, v116, v117 offset0:192 offset1:208
	ds_write2_b32 v45, v118, v119 offset0:224 offset1:240
	s_cmp_eq_u32 s0, 512
	s_cbranch_scc1 .Lrw_noprep
	s_waitcnt vmcnt(0)
	v_lshlrev_b32_e32 v48, 16, v34
	v_and_b32_e32 v49, 0xffff0000, v34
	v_lshlrev_b32_e32 v50, 16, v35
	v_and_b32_e32 v51, 0xffff0000, v35
	v_lshlrev_b32_e32 v52, 16, v36
	v_and_b32_e32 v53, 0xffff0000, v36
	v_lshlrev_b32_e32 v54, 16, v37
	v_and_b32_e32 v55, 0xffff0000, v37
	v_lshlrev_b32_e32 v56, 16, v38
	v_and_b32_e32 v57, 0xffff0000, v38
	v_lshlrev_b32_e32 v58, 16, v39
	v_and_b32_e32 v59, 0xffff0000, v39
	v_lshlrev_b32_e32 v60, 16, v40
	v_and_b32_e32 v61, 0xffff0000, v40
	v_lshlrev_b32_e32 v62, 16, v41
	v_and_b32_e32 v63, 0xffff0000, v41
	v_lshlrev_b32_e32 v64, 16, v42
	v_pk_mul_f32 v[68:69], v[52:53], v[16:17]
	v_pk_mul_f32 v[70:71], v[54:55], v[18:19]
	v_pk_mul_f32 v[72:73], v[68:69], v[68:69]
	v_pk_fma_f32 v[72:73], v[70:71], v[70:71], v[72:73]
	v_pk_add_f32 v[76:77], v[56:57], s[20:21]
	v_add_f32_e32 v74, v72, v73
	v_pk_add_f32 v[78:79], v[58:59], s[20:21]
	v_pk_mul_f32 v[84:85], v[60:61], s[22:23]
	v_add_f32_dpp v74, v74, v74 quad_perm:[1,0,3,2] row_mask:0xf bank_mask:0xf bound_ctrl:1
	v_pk_mul_f32 v[86:87], v[62:63], s[22:23]
	v_pk_fma_f32 v[76:77], v[76:77], v[20:21], s[30:31]
	v_add_f32_dpp v74, v74, v74 quad_perm:[2,3,0,1] row_mask:0xf bank_mask:0xf bound_ctrl:1
	v_pk_fma_f32 v[78:79], v[78:79], v[22:23], s[30:31]
	v_exp_f32_e32 v84, v84
	v_add_f32_dpp v74, v74, v74 row_half_mirror row_mask:0xf bank_mask:0xf bound_ctrl:1
	v_exp_f32_e32 v85, v85
	v_exp_f32_e32 v86, v86
	v_add_f32_dpp v74, v74, v74 row_mirror row_mask:0xf bank_mask:0xf bound_ctrl:1
	v_exp_f32_e32 v87, v87
	v_pk_mul_f32 v[80:81], v[52:53], v[76:77]
	v_add_f32_e32 v74, 0x358637bd, v74
	v_pk_mul_f32 v[82:83], v[54:55], v[78:79]
	v_rsq_f32_e32 v120, v74
	ds_write_b128 v43, v[84:87]
	ds_write_b128 v43, v[48:51] offset:16384
	ds_write_b32 v44, v64
	ds_write_b128 v43, v[80:83] offset:4096
	v_pk_mul_f32 v[124:125], v[68:69], v[120:121] op_sel_hi:[1,0] neg_lo:[0,1] neg_hi:[0,1]
	v_pk_mul_f32 v[126:127], v[70:71], v[120:121] op_sel_hi:[1,0] neg_lo:[0,1] neg_hi:[0,1]
	v_pk_mul_f32 v[100:101], v[124:125], v[56:57] neg_lo:[1,0] neg_hi:[1,0]
	v_pk_mul_f32 v[102:103], v[126:127], v[58:59] neg_lo:[1,0] neg_hi:[1,0]
	ds_write_b128 v43, v[124:127] offset:8192
	ds_write_b128 v43, v[100:103] offset:12288
	s_cmp_lg_u32 s18, 0
	s_cbranch_scc1 .Lrw_nosb_p1
	v_pk_mul_f32 v[104:105], v[48:49], v[80:81]
	v_pk_mul_f32 v[106:107], v[50:51], v[82:83]
	v_pk_mul_f32 v[108:109], v[104:105], v[24:25]
	v_pk_fma_f32 v[108:109], v[106:107], v[26:27], v[108:109]
	v_add_f32_e32 v110, v108, v109
	s_nop 1
	v_add_f32_dpp v110, v110, v110 quad_perm:[1,0,3,2] row_mask:0xf bank_mask:0xf bound_ctrl:1
	s_nop 1
	v_add_f32_dpp v110, v110, v110 quad_perm:[2,3,0,1] row_mask:0xf bank_mask:0xf bound_ctrl:1
	s_nop 1
	v_add_f32_dpp v110, v110, v110 row_half_mirror row_mask:0xf bank_mask:0xf bound_ctrl:1
	s_nop 1
	v_add_f32_dpp v110, v110, v110 row_mirror row_mask:0xf bank_mask:0xf bound_ctrl:1
	global_store_dword v33, v110, s[16:17]

; __device__ __forceinline__ void rwkv_item(const Params& p, int item, float* sm) {
;     ...
;     __syncthreads();
;     {
;       const float* bb = sm + bi * BUF;
;       const float yv = bb[5 * TC * 64 + TC * 16 + TC + ltt * 16 + lrr];
;       const float mu = dpp_sum16(yv) * (1.f / 16.f);
;       yr[(size_t)(t0 + ltt) * D + h * 64 + rg * 16 + lrr] = f2bf(yv - mu);
;       if (lrr == 0) MU[(rowb + t0 + ltt) * 64 + h * 4 + rg] = mu;
;     }
;   }
.Lrw_noprep:
	v_add_u32_e32 v46, s1, v135
	v_add_u32_e32 v10, s29, v47
	v_add_u32_e32 v11, s29, v136
	s_waitcnt lgkmcnt(0)
	s_barrier
	ds_read_b32 v120, v46
	ds_read_b128 v[56:59], v10 offset:8192
	ds_read_b128 v[48:51], v10
	ds_read_b128 v[52:55], v10 offset:4096
	ds_read_b128 v[60:63], v10 offset:12288
	ds_read_b128 v[80:83], v10 offset:16384
	ds_read_b128 v[88:91], v11 offset:0
	ds_read_b128 v[92:95], v11 offset:16
	ds_read_b128 v[96:99], v11 offset:32
	ds_read_b128 v[100:103], v11 offset:48
	ds_read_b128 v[72:75], v10 offset:8448
	ds_read_b128 v[64:67], v10 offset:256
	ds_read_b128 v[68:71], v10 offset:4352
	ds_read_b128 v[76:79], v10 offset:12544
	ds_read_b128 v[84:87], v10 offset:16640
	s_waitcnt lgkmcnt(14)
	v_add_f32_dpp v122, v120, v120 quad_perm:[1,0,3,2] row_mask:0xf bank_mask:0xf bound_ctrl:1
	s_nop 1
	v_add_f32_dpp v122, v122, v122 quad_perm:[2,3,0,1] row_mask:0xf bank_mask:0xf bound_ctrl:1
	s_nop 1
	v_add_f32_dpp v122, v122, v122 row_half_mirror row_mask:0xf bank_mask:0xf bound_ctrl:1
	s_nop 1
	v_add_f32_dpp v122, v122, v122 row_mirror row_mask:0xf bank_mask:0xf bound_ctrl:1
	s_nop 0
	v_fmac_f32_e32 v120, 0xbd800000, v122
	v_mul_f32_e32 v122, 0x3d800000, v122
	v_cvt_pk_bf16_f32 v124, v120, v120
	global_store_dword v32, v122, s[14:15]
	global_store_short v31, v124, s[10:11]
	s_add_u32 s10, s10, 0x8000
	s_addc_u32 s11, s11, 0
	s_add_u32 s14, s14, 0x1000
	s_addc_u32 s15, s15, 0
	s_mov_b32 s1, s29
	s_add_i32 s0, s0, 1
	s_cmp_lg_u32 s0, 513
	s_cbranch_scc1 .Lrw_chunk
	s_waitcnt lgkmcnt(0)
	s_branch .LBB0_504

; __device__ __forceinline__ void mixer0_phase(const Params& p, float* sm, int bid, int nb) {
;   const int nfox = NB * 8 * 33;
;   if (nb > 128) {
;     if (bid < 128) {
;       gdn_item(p, bid, sm);
;     } else {
;       for (int f = bid - 128; f < nfox; f += nb - 128) {
;         const int qt = 32 - f / 32, bh = f % 32;
;         fox_item(p, bh * 33 + qt, sm);
;       }
;     }
.LBB0_1681:
	s_andn2_b64 vcc, exec, s[0:1]
	s_cbranch_vccnz .LBB0_1747
	v_readlane_b32 s0, v244, 27
	s_cmpk_gt_i32 s0, 0x7f
	s_mov_b64 s[0:1], -1
	s_cbranch_scc0 .LBB0_1725
	v_readlane_b32 s0, v244, 27
	s_cmpk_gt_u32 s0, 0x49f
	s_cbranch_scc1 .LBB0_1724
	v_readlane_b32 s0, v244, 27
	s_branch .Lfx_next

; __device__ __forceinline__ void mixer0_phase(const Params& p, float* sm, int bid, int nb) {
;     ...
;       for (int f = bid - 128; f < nfox; f += nb - 128) {
;         const int qt = 32 - f / 32, bh = f % 32;
;         fox_item(p, bh * 33 + qt, sm);
.Lfx_next:
	s_barrier
	v_readlane_b32 s0, v247, 3
	v_readlane_b32 s1, v247, 4
	s_add_u32 s0, s0, 0x1ff18180
	s_addc_u32 s1, s1, 0
	v_mov_b32_e32 v122, 0x10000
	v_cmp_eq_u32_e32 vcc, 0, v2
	s_and_saveexec_b64 s[4:5], vcc
	s_cbranch_execz .Lfx_nb
	v_mov_b32_e32 v8, 1
	global_atomic_add v8, v9, v8, s[0:1] sc0
	s_waitcnt vmcnt(0)
	ds_write_b32 v122, v8
	s_waitcnt lgkmcnt(0)
.Lfx_nb:
	s_or_b64 exec, exec, s[4:5]
	s_barrier
	ds_read_b32 v8, v122
	s_waitcnt lgkmcnt(0)
	v_readfirstlane_b32 s52, v8
	s_cmpk_gt_i32 s52, 0x41f
	s_cbranch_scc1 .LBB0_1724

; __global__ void __launch_bounds__(256, 2) mega_kernel(Params p) {
;   __shared__ __attribute__((aligned(16))) char smraw[LDS_BYTES];
	.amdhsa_kernel _Z11mega_kernel6Params
		.amdhsa_group_segment_fixed_size 81920
		.amdhsa_private_segment_fixed_size 0
		.amdhsa_kernarg_size 528
		.amdhsa_user_sgpr_count 2
		.amdhsa_user_sgpr_dispatch_ptr 0
		.amdhsa_user_sgpr_queue_ptr 0
		.amdhsa_user_sgpr_kernarg_segment_ptr 1
		.amdhsa_user_sgpr_dispatch_id 0
		.amdhsa_user_sgpr_kernarg_preload_length 0
		.amdhsa_user_sgpr_kernarg_preload_offset 0
		.amdhsa_user_sgpr_private_segment_size 0
		.amdhsa_uses_dynamic_stack 0
		.amdhsa_enable_private_segment 0
		.amdhsa_system_sgpr_workgroup_id_x 1
		.amdhsa_system_sgpr_workgroup_id_y 0
		.amdhsa_system_sgpr_workgroup_id_z 0
		.amdhsa_system_sgpr_workgroup_info 0
		.amdhsa_system_vgpr_workitem_id 2
		.amdhsa_next_free_vgpr 248
		.amdhsa_next_free_sgpr 102
		.amdhsa_accum_offset 248
		.amdhsa_reserve_vcc 1
		.amdhsa_float_round_mode_32 0
		.amdhsa_float_round_mode_16_64 0
		.amdhsa_float_denorm_mode_32 3
		.amdhsa_float_denorm_mode_16_64 3
		.amdhsa_dx10_clamp 1
		.amdhsa_ieee_mode 1
		.amdhsa_fp16_overflow 0
		.amdhsa_tg_split 0
		.amdhsa_exception_fp_ieee_invalid_op 0
		.amdhsa_exception_fp_denorm_src 0
		.amdhsa_exception_fp_ieee_div_zero 0
		.amdhsa_exception_fp_ieee_overflow 0
		.amdhsa_exception_fp_ieee_underflow 0
		.amdhsa_exception_fp_ieee_inexact 0
		.amdhsa_exception_int_div_zero 0
	.end_amdhsa_kernel

; __global__ void __launch_bounds__(256, 2) mega_kernel(Params p) {
;   __shared__ __attribute__((aligned(16))) char smraw[LDS_BYTES];
amdhsa.kernels:
  - .agpr_count:     0
    .args:
      - .offset:         0
        .size:           272
        .value_kind:     by_value
      - .offset:         272
        .size:           4
        .value_kind:     hidden_block_count_x
      - .offset:         276
        .size:           4
        .value_kind:     hidden_block_count_y
      - .offset:         280
        .size:           4
        .value_kind:     hidden_block_count_z
      - .offset:         284
        .size:           2
        .value_kind:     hidden_group_size_x
      - .offset:         286
        .size:           2
        .value_kind:     hidden_group_size_y
      - .offset:         288
        .size:           2
        .value_kind:     hidden_group_size_z
      - .offset:         290
        .size:           2
        .value_kind:     hidden_remainder_x
      - .offset:         292
        .size:           2
        .value_kind:     hidden_remainder_y
      - .offset:         294
        .size:           2
        .value_kind:     hidden_remainder_z
      - .offset:         312
        .size:           8
        .value_kind:     hidden_global_offset_x
      - .offset:         320
        .size:           8
        .value_kind:     hidden_global_offset_y
      - .offset:         328
        .size:           8
        .value_kind:     hidden_global_offset_z
      - .offset:         336
        .size:           2
        .value_kind:     hidden_grid_dims
      - .offset:         360
        .size:           8
        .value_kind:     hidden_multigrid_sync_arg
    .group_segment_fixed_size: 81920
    .kernarg_segment_align: 8
    .kernarg_segment_size: 528
    .language:       OpenCL C
    .language_version:
      - 2
      - 0
    .max_flat_workgroup_size: 256
    .name:           _Z11mega_kernel6Params
    .private_segment_fixed_size: 0
    .sgpr_count:     108
    .sgpr_spill_count: 478
    .symbol:         _Z11mega_kernel6Params.kd
    .uniform_work_group_size: 1
    .uses_dynamic_stack: false
    .vgpr_count:     248
    .vgpr_spill_count: 0
    .wavefront_size: 64
